# in-proj layer-1 last round: 4-way K split (8 K-tiles per workgroup, 3 partial hand-overs per tile) instead of 2-way (on v86)
# baseline (speedup 1.0000x reference)
.LBB0_81:
	s_add_i32 s62, s62, 1
	s_mul_i32 s4, s62, s31
	s_mul_hi_u32 s5, s62, s82
	s_add_i32 s5, s5, s4
	s_mul_i32 s4, s62, s82
	s_add_u32 s4, s4, s2
	s_addc_u32 s5, s5, s3
	s_waitcnt lgkmcnt(0)
	s_mov_b32 s99, 0
	s_add_i32 s100, s88, -1
	s_lshr_b32 s100, s100, 8
	s_cmp_lg_u32 s62, s100
	s_cbranch_scc1 .Lmy_ik_nosplit
	s_lshl_b32 s101, s100, 8
	s_sub_i32 s100, s88, s101
	s_cmpk_gt_i32 s100, 48
	s_cbranch_scc1 .Lmy_ik_nosplit
	s_lshl_b32 s100, s100, 2
	s_mov_b32 s4, s88
	s_cmp_lt_u32 s2, s100
	s_cbranch_scc0 .Lmy_ik_nosplit
	s_lshr_b32 s4, s2, 2
	s_add_i32 s4, s4, s101
	s_and_b32 s99, s2, 3
	s_add_i32 s99, s99, 1

.LBB0_90:
	s_ashr_i32 s7, s6, 31
	s_lshl_b64 s[4:5], s[6:7], 20
	s_cmp_eq_u32 s63, 0
	s_cselect_b32 s45, s80, s54
	s_cselect_b32 s7, s81, s37
	s_cselect_b32 s65, s59, s80
	s_cselect_b32 s66, s58, s81
	s_add_u32 s46, s45, s4
	s_addc_u32 s47, s7, s5
	s_sub_i32 s100, s99, 1
	s_max_i32 s100, s100, 0
	s_lshl_b32 s100, s100, 10
	s_add_u32 s46, s46, s100
	s_addc_u32 s47, s47, 0
	s_and_b64 s[4:5], s[40:41], exec
	s_cselect_b32 s7, s47, s43
	s_cselect_b32 s45, s46, s42
	s_ashr_i32 s95, s94, 31
	s_lshl_b64 s[4:5], s[94:95], 20
	s_add_u32 s4, s65, s4
	s_addc_u32 s5, s66, s5
	s_add_u32 s4, s4, s100
	s_addc_u32 s5, s5, 0
	s_and_b64 s[66:67], s[40:41], exec
	s_cselect_b32 s65, s5, s9
	s_cselect_b32 s66, s4, s8
	s_add_u32 s42, s42, 0x80080
	s_addc_u32 s43, s43, 0
	s_add_u32 s67, s8, 0x100
	v_mov_b32_e32 v2, 0
	s_addc_u32 s68, s9, 0
	s_cmp_eq_u32 s98, 0
	s_cselect_b32 s69, -2, 22
	v_mov_b32_e32 v3, v2
	v_mov_b32_e32 v4, v2
	v_mov_b32_e32 v5, v2
	v_mov_b32_e32 v6, v2
	v_mov_b32_e32 v7, v2
	v_mov_b32_e32 v8, v2
	v_mov_b32_e32 v9, v2
	v_mov_b32_e32 v18, v2
	v_mov_b32_e32 v19, v2
	v_mov_b32_e32 v20, v2
	v_mov_b32_e32 v21, v2
	v_mov_b32_e32 v22, v2
	v_mov_b32_e32 v23, v2
	v_mov_b32_e32 v24, v2
	v_mov_b32_e32 v25, v2
	v_mov_b32_e32 v34, v2
	v_mov_b32_e32 v35, v2
	v_mov_b32_e32 v36, v2
	v_mov_b32_e32 v37, v2
	v_mov_b32_e32 v38, v2
	v_mov_b32_e32 v39, v2
	v_mov_b32_e32 v40, v2
	v_mov_b32_e32 v41, v2
	v_mov_b32_e32 v50, v2
	v_mov_b32_e32 v51, v2
	v_mov_b32_e32 v52, v2
	v_mov_b32_e32 v53, v2
	v_mov_b32_e32 v54, v2
	v_mov_b32_e32 v55, v2
	v_mov_b32_e32 v56, v2
	v_mov_b32_e32 v57, v2
	v_mov_b32_e32 v10, v2
	v_mov_b32_e32 v11, v2
	v_mov_b32_e32 v12, v2
	v_mov_b32_e32 v13, v2
	v_mov_b32_e32 v14, v2
	v_mov_b32_e32 v15, v2
	v_mov_b32_e32 v16, v2
	v_mov_b32_e32 v17, v2
	v_mov_b32_e32 v26, v2
	v_mov_b32_e32 v27, v2
	v_mov_b32_e32 v28, v2
	v_mov_b32_e32 v29, v2
	v_mov_b32_e32 v30, v2
	v_mov_b32_e32 v31, v2
	v_mov_b32_e32 v32, v2
	v_mov_b32_e32 v33, v2
	v_mov_b32_e32 v42, v2
	v_mov_b32_e32 v43, v2
	v_mov_b32_e32 v44, v2
	v_mov_b32_e32 v45, v2
	v_mov_b32_e32 v46, v2
	v_mov_b32_e32 v47, v2
	v_mov_b32_e32 v48, v2
	v_mov_b32_e32 v49, v2
	v_mov_b32_e32 v58, v2
	v_mov_b32_e32 v59, v2
	v_mov_b32_e32 v60, v2
	v_mov_b32_e32 v61, v2
	v_mov_b32_e32 v62, v2
	v_mov_b32_e32 v63, v2
	v_mov_b32_e32 v64, v2
	v_mov_b32_e32 v65, v2
	v_mov_b32_e32 v66, v2
	v_mov_b32_e32 v67, v2
	v_mov_b32_e32 v68, v2
	v_mov_b32_e32 v69, v2
	v_mov_b32_e32 v70, v2
	v_mov_b32_e32 v71, v2
	v_mov_b32_e32 v72, v2
	v_mov_b32_e32 v73, v2
	v_mov_b32_e32 v82, v2
	v_mov_b32_e32 v83, v2
	v_mov_b32_e32 v84, v2
	v_mov_b32_e32 v85, v2
	v_mov_b32_e32 v86, v2
	v_mov_b32_e32 v87, v2
	v_mov_b32_e32 v88, v2
	v_mov_b32_e32 v89, v2
	v_mov_b32_e32 v98, v2
	v_mov_b32_e32 v99, v2
	v_mov_b32_e32 v100, v2
	v_mov_b32_e32 v101, v2
	v_mov_b32_e32 v102, v2
	v_mov_b32_e32 v103, v2
	v_mov_b32_e32 v104, v2
	v_mov_b32_e32 v105, v2
	v_mov_b32_e32 v120, v2
	v_mov_b32_e32 v121, v2
	v_mov_b32_e32 v122, v2
	v_mov_b32_e32 v123, v2
	v_mov_b32_e32 v124, v2
	v_mov_b32_e32 v125, v2
	v_mov_b32_e32 v126, v2
	v_mov_b32_e32 v127, v2
	v_mov_b32_e32 v74, v2
	v_mov_b32_e32 v75, v2
	v_mov_b32_e32 v76, v2
	v_mov_b32_e32 v77, v2
	v_mov_b32_e32 v78, v2
	v_mov_b32_e32 v79, v2
	v_mov_b32_e32 v80, v2
	v_mov_b32_e32 v81, v2
	v_mov_b32_e32 v90, v2
	v_mov_b32_e32 v91, v2
	v_mov_b32_e32 v92, v2
	v_mov_b32_e32 v93, v2
	v_mov_b32_e32 v94, v2
	v_mov_b32_e32 v95, v2
	v_mov_b32_e32 v96, v2
	v_mov_b32_e32 v97, v2
	v_mov_b32_e32 v106, v2
	v_mov_b32_e32 v107, v2
	v_mov_b32_e32 v108, v2
	v_mov_b32_e32 v109, v2
	v_mov_b32_e32 v116, v2
	v_mov_b32_e32 v117, v2
	v_mov_b32_e32 v118, v2
	v_mov_b32_e32 v119, v2
	v_mov_b32_e32 v128, v2
	v_mov_b32_e32 v129, v2
	v_mov_b32_e32 v130, v2
	v_mov_b32_e32 v131, v2
	v_mov_b32_e32 v132, v2
	v_mov_b32_e32 v133, v2
	v_mov_b32_e32 v134, v2
	v_mov_b32_e32 v135, v2

.LBB0_94:
	s_cmp_eq_u32 s98, 0
	s_cbranch_scc1 .Lmy_ik_norm
	s_cmp_eq_u32 s98, 1
	s_cbranch_scc1 .Lmy_ik_cons
	s_branch .Lmy_ik_prod
.Lmy_ik_prod:
	s_lshr_b32 s100, s2, 2
	s_mul_i32 s100, s100, 3
	s_add_i32 s100, s100, s98
	s_add_i32 s100, s100, -2
	s_lshl_b32 s100, s100, 18
	s_add_u32 s100, s76, s100
	s_addc_u32 s101, s77, 0
	s_add_u32 s100, s100, 0x1a900000
	s_addc_u32 s101, s101, 0
	v_readfirstlane_b32 s99, v164
	s_lshr_b32 s99, s99, 6
	s_lshl_b32 s99, s99, 15
	s_add_u32 s100, s100, s99
	s_addc_u32 s101, s101, 0
	v_lshlrev_b32_e32 v250, 4, v202
	global_store_dwordx4 v250, v[132:135], s[100:101] sc0 sc1
	global_store_dwordx4 v250, v[128:131], s[100:101] offset:1024 sc0 sc1
	global_store_dwordx4 v250, v[116:119], s[100:101] offset:2048 sc0 sc1
	global_store_dwordx4 v250, v[106:109], s[100:101] offset:3072 sc0 sc1
	s_add_u32 s100, s100, 0x1000
	s_addc_u32 s101, s101, 0
	global_store_dwordx4 v250, v[94:97], s[100:101] sc0 sc1
	global_store_dwordx4 v250, v[90:93], s[100:101] offset:1024 sc0 sc1
	global_store_dwordx4 v250, v[78:81], s[100:101] offset:2048 sc0 sc1
	global_store_dwordx4 v250, v[74:77], s[100:101] offset:3072 sc0 sc1
	s_add_u32 s100, s100, 0x1000
	s_addc_u32 s101, s101, 0
	global_store_dwordx4 v250, v[124:127], s[100:101] sc0 sc1
	global_store_dwordx4 v250, v[120:123], s[100:101] offset:1024 sc0 sc1
	global_store_dwordx4 v250, v[102:105], s[100:101] offset:2048 sc0 sc1
	global_store_dwordx4 v250, v[98:101], s[100:101] offset:3072 sc0 sc1
	s_add_u32 s100, s100, 0x1000
	s_addc_u32 s101, s101, 0
	global_store_dwordx4 v250, v[86:89], s[100:101] sc0 sc1
	global_store_dwordx4 v250, v[82:85], s[100:101] offset:1024 sc0 sc1
	global_store_dwordx4 v250, v[70:73], s[100:101] offset:2048 sc0 sc1
	global_store_dwordx4 v250, v[66:69], s[100:101] offset:3072 sc0 sc1
	s_add_u32 s100, s100, 0x1000
	s_addc_u32 s101, s101, 0
	global_store_dwordx4 v250, v[62:65], s[100:101] sc0 sc1
	global_store_dwordx4 v250, v[58:61], s[100:101] offset:1024 sc0 sc1
	global_store_dwordx4 v250, v[46:49], s[100:101] offset:2048 sc0 sc1
	global_store_dwordx4 v250, v[42:45], s[100:101] offset:3072 sc0 sc1
	s_add_u32 s100, s100, 0x1000
	s_addc_u32 s101, s101, 0
	global_store_dwordx4 v250, v[30:33], s[100:101] sc0 sc1
	global_store_dwordx4 v250, v[26:29], s[100:101] offset:1024 sc0 sc1
	global_store_dwordx4 v250, v[14:17], s[100:101] offset:2048 sc0 sc1
	global_store_dwordx4 v250, v[10:13], s[100:101] offset:3072 sc0 sc1
	s_add_u32 s100, s100, 0x1000
	s_addc_u32 s101, s101, 0
	global_store_dwordx4 v250, v[54:57], s[100:101] sc0 sc1
	global_store_dwordx4 v250, v[50:53], s[100:101] offset:1024 sc0 sc1
	global_store_dwordx4 v250, v[38:41], s[100:101] offset:2048 sc0 sc1
	global_store_dwordx4 v250, v[34:37], s[100:101] offset:3072 sc0 sc1
	s_add_u32 s100, s100, 0x1000
	s_addc_u32 s101, s101, 0
	global_store_dwordx4 v250, v[22:25], s[100:101] sc0 sc1
	global_store_dwordx4 v250, v[18:21], s[100:101] offset:1024 sc0 sc1
	global_store_dwordx4 v250, v[6:9], s[100:101] offset:2048 sc0 sc1
	global_store_dwordx4 v250, v[2:5], s[100:101] offset:3072 sc0 sc1
	s_waitcnt vmcnt(0)
	s_barrier
	v_cmp_eq_u32_e32 vcc, 0, v164
	s_and_saveexec_b64 s[100:101], vcc
	s_cbranch_execz .Lmy_ik_pflag
	s_lshr_b32 s99, s2, 2
	s_lshl_b32 s99, s99, 2
	v_mov_b32_e32 v250, s99
	v_mov_b32_e32 v251, 1
	global_atomic_add v250, v251, s[76:77] offset:256 sc1

.Lmy_ik_cons:
	v_cmp_eq_u32_e32 vcc, 0, v164
	s_and_saveexec_b64 s[100:101], vcc
	s_cbranch_execz .Lmy_ik_cgot2
	s_lshr_b32 s99, s2, 2
	s_lshl_b32 s99, s99, 2
	v_mov_b32_e32 v250, s99
	s_mov_b32 s99, 0
.Lmy_ik_spin:
	global_load_dword v251, v250, s[76:77] offset:256 sc1
	s_waitcnt vmcnt(0)
	v_readfirstlane_b32 vcc_lo, v251
	s_cmp_eq_u32 vcc_lo, 3
	s_cbranch_scc1 .Lmy_ik_cgot
	s_sleep 1
	s_add_i32 s99, s99, 1
	s_cmpk_lt_u32 s99, 0x4000
	s_cbranch_scc1 .Lmy_ik_spin

.Lmy_ik_cgot2:
	s_or_b64 exec, exec, s[100:101]
	s_waitcnt vmcnt(0)
	s_barrier
	buffer_inv sc1
	s_lshr_b32 s100, s2, 2
	s_mul_i32 s100, s100, 3
	s_lshl_b32 s100, s100, 18
	s_add_u32 s100, s76, s100
	s_addc_u32 s101, s77, 0
	s_add_u32 s100, s100, 0x1a900000
	s_addc_u32 s101, s101, 0
	v_readfirstlane_b32 s99, v164
	s_lshr_b32 s99, s99, 6
	s_lshl_b32 s99, s99, 15
	s_add_u32 s100, s100, s99
	s_addc_u32 s101, s101, 0
	v_lshlrev_b32_e32 v250, 4, v202
	global_load_dwordx4 v[216:219], v250, s[100:101] sc0 sc1
	global_load_dwordx4 v[220:223], v250, s[100:101] offset:1024 sc0 sc1
	global_load_dwordx4 v[224:227], v250, s[100:101] offset:2048 sc0 sc1
	global_load_dwordx4 v[228:231], v250, s[100:101] offset:3072 sc0 sc1
	s_add_u32 s100, s100, 0x1000
	s_addc_u32 s101, s101, 0
	global_load_dwordx4 v[232:235], v250, s[100:101] sc0 sc1
	global_load_dwordx4 v[236:239], v250, s[100:101] offset:1024 sc0 sc1
	global_load_dwordx4 v[240:243], v250, s[100:101] offset:2048 sc0 sc1
	global_load_dwordx4 v[136:139], v250, s[100:101] offset:3072 sc0 sc1
	s_add_u32 s100, s100, 0x1000
	s_addc_u32 s101, s101, 0
	s_waitcnt vmcnt(7)
	v_pk_add_f32 v[132:133], v[132:133], v[216:217]
	v_pk_add_f32 v[134:135], v[134:135], v[218:219]
	s_waitcnt vmcnt(6)
	v_pk_add_f32 v[128:129], v[128:129], v[220:221]
	v_pk_add_f32 v[130:131], v[130:131], v[222:223]
	s_waitcnt vmcnt(5)
	v_pk_add_f32 v[116:117], v[116:117], v[224:225]
	v_pk_add_f32 v[118:119], v[118:119], v[226:227]
	s_waitcnt vmcnt(4)
	v_pk_add_f32 v[106:107], v[106:107], v[228:229]
	v_pk_add_f32 v[108:109], v[108:109], v[230:231]
	s_waitcnt vmcnt(3)
	v_pk_add_f32 v[94:95], v[94:95], v[232:233]
	v_pk_add_f32 v[96:97], v[96:97], v[234:235]
	s_waitcnt vmcnt(2)
	v_pk_add_f32 v[90:91], v[90:91], v[236:237]
	v_pk_add_f32 v[92:93], v[92:93], v[238:239]
	s_waitcnt vmcnt(1)
	v_pk_add_f32 v[78:79], v[78:79], v[240:241]
	v_pk_add_f32 v[80:81], v[80:81], v[242:243]
	s_waitcnt vmcnt(0)
	v_pk_add_f32 v[74:75], v[74:75], v[136:137]
	v_pk_add_f32 v[76:77], v[76:77], v[138:139]
	global_load_dwordx4 v[216:219], v250, s[100:101] sc0 sc1
	global_load_dwordx4 v[220:223], v250, s[100:101] offset:1024 sc0 sc1
	global_load_dwordx4 v[224:227], v250, s[100:101] offset:2048 sc0 sc1
	global_load_dwordx4 v[228:231], v250, s[100:101] offset:3072 sc0 sc1
	s_add_u32 s100, s100, 0x1000
	s_addc_u32 s101, s101, 0
	global_load_dwordx4 v[232:235], v250, s[100:101] sc0 sc1
	global_load_dwordx4 v[236:239], v250, s[100:101] offset:1024 sc0 sc1
	global_load_dwordx4 v[240:243], v250, s[100:101] offset:2048 sc0 sc1
	global_load_dwordx4 v[136:139], v250, s[100:101] offset:3072 sc0 sc1
	s_add_u32 s100, s100, 0x1000
	s_addc_u32 s101, s101, 0
	s_waitcnt vmcnt(7)
	v_pk_add_f32 v[124:125], v[124:125], v[216:217]
	v_pk_add_f32 v[126:127], v[126:127], v[218:219]
	s_waitcnt vmcnt(6)
	v_pk_add_f32 v[120:121], v[120:121], v[220:221]
	v_pk_add_f32 v[122:123], v[122:123], v[222:223]
	s_waitcnt vmcnt(5)
	v_pk_add_f32 v[102:103], v[102:103], v[224:225]
	v_pk_add_f32 v[104:105], v[104:105], v[226:227]
	s_waitcnt vmcnt(4)
	v_pk_add_f32 v[98:99], v[98:99], v[228:229]
	v_pk_add_f32 v[100:101], v[100:101], v[230:231]
	s_waitcnt vmcnt(3)
	v_pk_add_f32 v[86:87], v[86:87], v[232:233]
	v_pk_add_f32 v[88:89], v[88:89], v[234:235]
	s_waitcnt vmcnt(2)
	v_pk_add_f32 v[82:83], v[82:83], v[236:237]
	v_pk_add_f32 v[84:85], v[84:85], v[238:239]
	s_waitcnt vmcnt(1)
	v_pk_add_f32 v[70:71], v[70:71], v[240:241]
	v_pk_add_f32 v[72:73], v[72:73], v[242:243]
	s_waitcnt vmcnt(0)
	v_pk_add_f32 v[66:67], v[66:67], v[136:137]
	v_pk_add_f32 v[68:69], v[68:69], v[138:139]
	global_load_dwordx4 v[216:219], v250, s[100:101] sc0 sc1
	global_load_dwordx4 v[220:223], v250, s[100:101] offset:1024 sc0 sc1
	global_load_dwordx4 v[224:227], v250, s[100:101] offset:2048 sc0 sc1
	global_load_dwordx4 v[228:231], v250, s[100:101] offset:3072 sc0 sc1
	s_add_u32 s100, s100, 0x1000
	s_addc_u32 s101, s101, 0
	global_load_dwordx4 v[232:235], v250, s[100:101] sc0 sc1
	global_load_dwordx4 v[236:239], v250, s[100:101] offset:1024 sc0 sc1
	global_load_dwordx4 v[240:243], v250, s[100:101] offset:2048 sc0 sc1
	global_load_dwordx4 v[136:139], v250, s[100:101] offset:3072 sc0 sc1
	s_add_u32 s100, s100, 0x1000
	s_addc_u32 s101, s101, 0
	s_waitcnt vmcnt(7)
	v_pk_add_f32 v[62:63], v[62:63], v[216:217]
	v_pk_add_f32 v[64:65], v[64:65], v[218:219]
	s_waitcnt vmcnt(6)
	v_pk_add_f32 v[58:59], v[58:59], v[220:221]
	v_pk_add_f32 v[60:61], v[60:61], v[222:223]
	s_waitcnt vmcnt(5)
	v_pk_add_f32 v[46:47], v[46:47], v[224:225]
	v_pk_add_f32 v[48:49], v[48:49], v[226:227]
	s_waitcnt vmcnt(4)
	v_pk_add_f32 v[42:43], v[42:43], v[228:229]
	v_pk_add_f32 v[44:45], v[44:45], v[230:231]
	s_waitcnt vmcnt(3)
	v_pk_add_f32 v[30:31], v[30:31], v[232:233]
	v_pk_add_f32 v[32:33], v[32:33], v[234:235]
	s_waitcnt vmcnt(2)
	v_pk_add_f32 v[26:27], v[26:27], v[236:237]
	v_pk_add_f32 v[28:29], v[28:29], v[238:239]
	s_waitcnt vmcnt(1)
	v_pk_add_f32 v[14:15], v[14:15], v[240:241]
	v_pk_add_f32 v[16:17], v[16:17], v[242:243]
	s_waitcnt vmcnt(0)
	v_pk_add_f32 v[10:11], v[10:11], v[136:137]
	v_pk_add_f32 v[12:13], v[12:13], v[138:139]
	global_load_dwordx4 v[216:219], v250, s[100:101] sc0 sc1
	global_load_dwordx4 v[220:223], v250, s[100:101] offset:1024 sc0 sc1
	global_load_dwordx4 v[224:227], v250, s[100:101] offset:2048 sc0 sc1
	global_load_dwordx4 v[228:231], v250, s[100:101] offset:3072 sc0 sc1
	s_add_u32 s100, s100, 0x1000
	s_addc_u32 s101, s101, 0
	global_load_dwordx4 v[232:235], v250, s[100:101] sc0 sc1
	global_load_dwordx4 v[236:239], v250, s[100:101] offset:1024 sc0 sc1
	global_load_dwordx4 v[240:243], v250, s[100:101] offset:2048 sc0 sc1
	global_load_dwordx4 v[136:139], v250, s[100:101] offset:3072 sc0 sc1
	s_add_u32 s100, s100, 0x1000
	s_addc_u32 s101, s101, 0
	s_waitcnt vmcnt(7)
	v_pk_add_f32 v[54:55], v[54:55], v[216:217]
	v_pk_add_f32 v[56:57], v[56:57], v[218:219]
	s_waitcnt vmcnt(6)
	v_pk_add_f32 v[50:51], v[50:51], v[220:221]
	v_pk_add_f32 v[52:53], v[52:53], v[222:223]
	s_waitcnt vmcnt(5)
	v_pk_add_f32 v[38:39], v[38:39], v[224:225]
	v_pk_add_f32 v[40:41], v[40:41], v[226:227]
	s_waitcnt vmcnt(4)
	v_pk_add_f32 v[34:35], v[34:35], v[228:229]
	v_pk_add_f32 v[36:37], v[36:37], v[230:231]
	s_waitcnt vmcnt(3)
	v_pk_add_f32 v[22:23], v[22:23], v[232:233]
	v_pk_add_f32 v[24:25], v[24:25], v[234:235]
	s_waitcnt vmcnt(2)
	v_pk_add_f32 v[18:19], v[18:19], v[236:237]
	v_pk_add_f32 v[20:21], v[20:21], v[238:239]
	s_waitcnt vmcnt(1)
	v_pk_add_f32 v[6:7], v[6:7], v[240:241]
	v_pk_add_f32 v[8:9], v[8:9], v[242:243]
	s_waitcnt vmcnt(0)
	v_pk_add_f32 v[2:3], v[2:3], v[136:137]
	v_pk_add_f32 v[4:5], v[4:5], v[138:139]
	s_add_u32 s100, s100, 0x38000
	s_addc_u32 s101, s101, 0
	global_load_dwordx4 v[216:219], v250, s[100:101] sc0 sc1
	global_load_dwordx4 v[220:223], v250, s[100:101] offset:1024 sc0 sc1
	global_load_dwordx4 v[224:227], v250, s[100:101] offset:2048 sc0 sc1
	global_load_dwordx4 v[228:231], v250, s[100:101] offset:3072 sc0 sc1
	s_add_u32 s100, s100, 0x1000
	s_addc_u32 s101, s101, 0
	global_load_dwordx4 v[232:235], v250, s[100:101] sc0 sc1
	global_load_dwordx4 v[236:239], v250, s[100:101] offset:1024 sc0 sc1
	global_load_dwordx4 v[240:243], v250, s[100:101] offset:2048 sc0 sc1
	global_load_dwordx4 v[136:139], v250, s[100:101] offset:3072 sc0 sc1
	s_add_u32 s100, s100, 0x1000
	s_addc_u32 s101, s101, 0
	s_waitcnt vmcnt(7)
	v_pk_add_f32 v[132:133], v[132:133], v[216:217]
	v_pk_add_f32 v[134:135], v[134:135], v[218:219]
	s_waitcnt vmcnt(6)
	v_pk_add_f32 v[128:129], v[128:129], v[220:221]
	v_pk_add_f32 v[130:131], v[130:131], v[222:223]
	s_waitcnt vmcnt(5)
	v_pk_add_f32 v[116:117], v[116:117], v[224:225]
	v_pk_add_f32 v[118:119], v[118:119], v[226:227]
	s_waitcnt vmcnt(4)
	v_pk_add_f32 v[106:107], v[106:107], v[228:229]
	v_pk_add_f32 v[108:109], v[108:109], v[230:231]
	s_waitcnt vmcnt(3)
	v_pk_add_f32 v[94:95], v[94:95], v[232:233]
	v_pk_add_f32 v[96:97], v[96:97], v[234:235]
	s_waitcnt vmcnt(2)
	v_pk_add_f32 v[90:91], v[90:91], v[236:237]
	v_pk_add_f32 v[92:93], v[92:93], v[238:239]
	s_waitcnt vmcnt(1)
	v_pk_add_f32 v[78:79], v[78:79], v[240:241]
	v_pk_add_f32 v[80:81], v[80:81], v[242:243]
	s_waitcnt vmcnt(0)
	v_pk_add_f32 v[74:75], v[74:75], v[136:137]
	v_pk_add_f32 v[76:77], v[76:77], v[138:139]
	global_load_dwordx4 v[216:219], v250, s[100:101] sc0 sc1
	global_load_dwordx4 v[220:223], v250, s[100:101] offset:1024 sc0 sc1
	global_load_dwordx4 v[224:227], v250, s[100:101] offset:2048 sc0 sc1
	global_load_dwordx4 v[228:231], v250, s[100:101] offset:3072 sc0 sc1
	s_add_u32 s100, s100, 0x1000
	s_addc_u32 s101, s101, 0
	global_load_dwordx4 v[232:235], v250, s[100:101] sc0 sc1
	global_load_dwordx4 v[236:239], v250, s[100:101] offset:1024 sc0 sc1
	global_load_dwordx4 v[240:243], v250, s[100:101] offset:2048 sc0 sc1
	global_load_dwordx4 v[136:139], v250, s[100:101] offset:3072 sc0 sc1
	s_add_u32 s100, s100, 0x1000
	s_addc_u32 s101, s101, 0
	s_waitcnt vmcnt(7)
	v_pk_add_f32 v[124:125], v[124:125], v[216:217]
	v_pk_add_f32 v[126:127], v[126:127], v[218:219]
	s_waitcnt vmcnt(6)
	v_pk_add_f32 v[120:121], v[120:121], v[220:221]
	v_pk_add_f32 v[122:123], v[122:123], v[222:223]
	s_waitcnt vmcnt(5)
	v_pk_add_f32 v[102:103], v[102:103], v[224:225]
	v_pk_add_f32 v[104:105], v[104:105], v[226:227]
	s_waitcnt vmcnt(4)
	v_pk_add_f32 v[98:99], v[98:99], v[228:229]
	v_pk_add_f32 v[100:101], v[100:101], v[230:231]
	s_waitcnt vmcnt(3)
	v_pk_add_f32 v[86:87], v[86:87], v[232:233]
	v_pk_add_f32 v[88:89], v[88:89], v[234:235]
	s_waitcnt vmcnt(2)
	v_pk_add_f32 v[82:83], v[82:83], v[236:237]
	v_pk_add_f32 v[84:85], v[84:85], v[238:239]
	s_waitcnt vmcnt(1)
	v_pk_add_f32 v[70:71], v[70:71], v[240:241]
	v_pk_add_f32 v[72:73], v[72:73], v[242:243]
	s_waitcnt vmcnt(0)
	v_pk_add_f32 v[66:67], v[66:67], v[136:137]
	v_pk_add_f32 v[68:69], v[68:69], v[138:139]
	global_load_dwordx4 v[216:219], v250, s[100:101] sc0 sc1
	global_load_dwordx4 v[220:223], v250, s[100:101] offset:1024 sc0 sc1
	global_load_dwordx4 v[224:227], v250, s[100:101] offset:2048 sc0 sc1
	global_load_dwordx4 v[228:231], v250, s[100:101] offset:3072 sc0 sc1
	s_add_u32 s100, s100, 0x1000
	s_addc_u32 s101, s101, 0
	global_load_dwordx4 v[232:235], v250, s[100:101] sc0 sc1
	global_load_dwordx4 v[236:239], v250, s[100:101] offset:1024 sc0 sc1
	global_load_dwordx4 v[240:243], v250, s[100:101] offset:2048 sc0 sc1
	global_load_dwordx4 v[136:139], v250, s[100:101] offset:3072 sc0 sc1
	s_add_u32 s100, s100, 0x1000
	s_addc_u32 s101, s101, 0
	s_waitcnt vmcnt(7)
	v_pk_add_f32 v[62:63], v[62:63], v[216:217]
	v_pk_add_f32 v[64:65], v[64:65], v[218:219]
	s_waitcnt vmcnt(6)
	v_pk_add_f32 v[58:59], v[58:59], v[220:221]
	v_pk_add_f32 v[60:61], v[60:61], v[222:223]
	s_waitcnt vmcnt(5)
	v_pk_add_f32 v[46:47], v[46:47], v[224:225]
	v_pk_add_f32 v[48:49], v[48:49], v[226:227]
	s_waitcnt vmcnt(4)
	v_pk_add_f32 v[42:43], v[42:43], v[228:229]
	v_pk_add_f32 v[44:45], v[44:45], v[230:231]
	s_waitcnt vmcnt(3)
	v_pk_add_f32 v[30:31], v[30:31], v[232:233]
	v_pk_add_f32 v[32:33], v[32:33], v[234:235]
	s_waitcnt vmcnt(2)
	v_pk_add_f32 v[26:27], v[26:27], v[236:237]
	v_pk_add_f32 v[28:29], v[28:29], v[238:239]
	s_waitcnt vmcnt(1)
	v_pk_add_f32 v[14:15], v[14:15], v[240:241]
	v_pk_add_f32 v[16:17], v[16:17], v[242:243]
	s_waitcnt vmcnt(0)
	v_pk_add_f32 v[10:11], v[10:11], v[136:137]
	v_pk_add_f32 v[12:13], v[12:13], v[138:139]
	global_load_dwordx4 v[216:219], v250, s[100:101] sc0 sc1
	global_load_dwordx4 v[220:223], v250, s[100:101] offset:1024 sc0 sc1
	global_load_dwordx4 v[224:227], v250, s[100:101] offset:2048 sc0 sc1
	global_load_dwordx4 v[228:231], v250, s[100:101] offset:3072 sc0 sc1
	s_add_u32 s100, s100, 0x1000
	s_addc_u32 s101, s101, 0
	global_load_dwordx4 v[232:235], v250, s[100:101] sc0 sc1
	global_load_dwordx4 v[236:239], v250, s[100:101] offset:1024 sc0 sc1
	global_load_dwordx4 v[240:243], v250, s[100:101] offset:2048 sc0 sc1
	global_load_dwordx4 v[136:139], v250, s[100:101] offset:3072 sc0 sc1
	s_add_u32 s100, s100, 0x1000
	s_addc_u32 s101, s101, 0
	s_waitcnt vmcnt(7)
	v_pk_add_f32 v[54:55], v[54:55], v[216:217]
	v_pk_add_f32 v[56:57], v[56:57], v[218:219]
	s_waitcnt vmcnt(6)
	v_pk_add_f32 v[50:51], v[50:51], v[220:221]
	v_pk_add_f32 v[52:53], v[52:53], v[222:223]
	s_waitcnt vmcnt(5)
	v_pk_add_f32 v[38:39], v[38:39], v[224:225]
	v_pk_add_f32 v[40:41], v[40:41], v[226:227]
	s_waitcnt vmcnt(4)
	v_pk_add_f32 v[34:35], v[34:35], v[228:229]
	v_pk_add_f32 v[36:37], v[36:37], v[230:231]
	s_waitcnt vmcnt(3)
	v_pk_add_f32 v[22:23], v[22:23], v[232:233]
	v_pk_add_f32 v[24:25], v[24:25], v[234:235]
	s_waitcnt vmcnt(2)
	v_pk_add_f32 v[18:19], v[18:19], v[236:237]
	v_pk_add_f32 v[20:21], v[20:21], v[238:239]
	s_waitcnt vmcnt(1)
	v_pk_add_f32 v[6:7], v[6:7], v[240:241]
	v_pk_add_f32 v[8:9], v[8:9], v[242:243]
	s_waitcnt vmcnt(0)
	v_pk_add_f32 v[2:3], v[2:3], v[136:137]
	v_pk_add_f32 v[4:5], v[4:5], v[138:139]
	s_add_u32 s100, s100, 0x38000
	s_addc_u32 s101, s101, 0
	global_load_dwordx4 v[216:219], v250, s[100:101] sc0 sc1
	global_load_dwordx4 v[220:223], v250, s[100:101] offset:1024 sc0 sc1
	global_load_dwordx4 v[224:227], v250, s[100:101] offset:2048 sc0 sc1
	global_load_dwordx4 v[228:231], v250, s[100:101] offset:3072 sc0 sc1
	s_add_u32 s100, s100, 0x1000
	s_addc_u32 s101, s101, 0
	global_load_dwordx4 v[232:235], v250, s[100:101] sc0 sc1
	global_load_dwordx4 v[236:239], v250, s[100:101] offset:1024 sc0 sc1
	global_load_dwordx4 v[240:243], v250, s[100:101] offset:2048 sc0 sc1
	global_load_dwordx4 v[136:139], v250, s[100:101] offset:3072 sc0 sc1
	s_add_u32 s100, s100, 0x1000
	s_addc_u32 s101, s101, 0
	s_waitcnt vmcnt(7)
	v_pk_add_f32 v[132:133], v[132:133], v[216:217]
	v_pk_add_f32 v[134:135], v[134:135], v[218:219]
	s_waitcnt vmcnt(6)
	v_pk_add_f32 v[128:129], v[128:129], v[220:221]
	v_pk_add_f32 v[130:131], v[130:131], v[222:223]
	s_waitcnt vmcnt(5)
	v_pk_add_f32 v[116:117], v[116:117], v[224:225]
	v_pk_add_f32 v[118:119], v[118:119], v[226:227]
	s_waitcnt vmcnt(4)
	v_pk_add_f32 v[106:107], v[106:107], v[228:229]
	v_pk_add_f32 v[108:109], v[108:109], v[230:231]
	s_waitcnt vmcnt(3)
	v_pk_add_f32 v[94:95], v[94:95], v[232:233]
	v_pk_add_f32 v[96:97], v[96:97], v[234:235]
	s_waitcnt vmcnt(2)
	v_pk_add_f32 v[90:91], v[90:91], v[236:237]
	v_pk_add_f32 v[92:93], v[92:93], v[238:239]
	s_waitcnt vmcnt(1)
	v_pk_add_f32 v[78:79], v[78:79], v[240:241]
	v_pk_add_f32 v[80:81], v[80:81], v[242:243]
	s_waitcnt vmcnt(0)
	v_pk_add_f32 v[74:75], v[74:75], v[136:137]
	v_pk_add_f32 v[76:77], v[76:77], v[138:139]
	global_load_dwordx4 v[216:219], v250, s[100:101] sc0 sc1
	global_load_dwordx4 v[220:223], v250, s[100:101] offset:1024 sc0 sc1
	global_load_dwordx4 v[224:227], v250, s[100:101] offset:2048 sc0 sc1
	global_load_dwordx4 v[228:231], v250, s[100:101] offset:3072 sc0 sc1
	s_add_u32 s100, s100, 0x1000
	s_addc_u32 s101, s101, 0
	global_load_dwordx4 v[232:235], v250, s[100:101] sc0 sc1
	global_load_dwordx4 v[236:239], v250, s[100:101] offset:1024 sc0 sc1
	global_load_dwordx4 v[240:243], v250, s[100:101] offset:2048 sc0 sc1
	global_load_dwordx4 v[136:139], v250, s[100:101] offset:3072 sc0 sc1
	s_add_u32 s100, s100, 0x1000
	s_addc_u32 s101, s101, 0
	s_waitcnt vmcnt(7)
	v_pk_add_f32 v[124:125], v[124:125], v[216:217]
	v_pk_add_f32 v[126:127], v[126:127], v[218:219]
	s_waitcnt vmcnt(6)
	v_pk_add_f32 v[120:121], v[120:121], v[220:221]
	v_pk_add_f32 v[122:123], v[122:123], v[222:223]
	s_waitcnt vmcnt(5)
	v_pk_add_f32 v[102:103], v[102:103], v[224:225]
	v_pk_add_f32 v[104:105], v[104:105], v[226:227]
	s_waitcnt vmcnt(4)
	v_pk_add_f32 v[98:99], v[98:99], v[228:229]
	v_pk_add_f32 v[100:101], v[100:101], v[230:231]
	s_waitcnt vmcnt(3)
	v_pk_add_f32 v[86:87], v[86:87], v[232:233]
	v_pk_add_f32 v[88:89], v[88:89], v[234:235]
	s_waitcnt vmcnt(2)
	v_pk_add_f32 v[82:83], v[82:83], v[236:237]
	v_pk_add_f32 v[84:85], v[84:85], v[238:239]
	s_waitcnt vmcnt(1)
	v_pk_add_f32 v[70:71], v[70:71], v[240:241]
	v_pk_add_f32 v[72:73], v[72:73], v[242:243]
	s_waitcnt vmcnt(0)
	v_pk_add_f32 v[66:67], v[66:67], v[136:137]
	v_pk_add_f32 v[68:69], v[68:69], v[138:139]
	global_load_dwordx4 v[216:219], v250, s[100:101] sc0 sc1
	global_load_dwordx4 v[220:223], v250, s[100:101] offset:1024 sc0 sc1
	global_load_dwordx4 v[224:227], v250, s[100:101] offset:2048 sc0 sc1
	global_load_dwordx4 v[228:231], v250, s[100:101] offset:3072 sc0 sc1
	s_add_u32 s100, s100, 0x1000
	s_addc_u32 s101, s101, 0
	global_load_dwordx4 v[232:235], v250, s[100:101] sc0 sc1
	global_load_dwordx4 v[236:239], v250, s[100:101] offset:1024 sc0 sc1
	global_load_dwordx4 v[240:243], v250, s[100:101] offset:2048 sc0 sc1
	global_load_dwordx4 v[136:139], v250, s[100:101] offset:3072 sc0 sc1
	s_add_u32 s100, s100, 0x1000
	s_addc_u32 s101, s101, 0
	s_waitcnt vmcnt(7)
	v_pk_add_f32 v[62:63], v[62:63], v[216:217]
	v_pk_add_f32 v[64:65], v[64:65], v[218:219]
	s_waitcnt vmcnt(6)
	v_pk_add_f32 v[58:59], v[58:59], v[220:221]
	v_pk_add_f32 v[60:61], v[60:61], v[222:223]
	s_waitcnt vmcnt(5)
	v_pk_add_f32 v[46:47], v[46:47], v[224:225]
	v_pk_add_f32 v[48:49], v[48:49], v[226:227]
	s_waitcnt vmcnt(4)
	v_pk_add_f32 v[42:43], v[42:43], v[228:229]
	v_pk_add_f32 v[44:45], v[44:45], v[230:231]
	s_waitcnt vmcnt(3)
	v_pk_add_f32 v[30:31], v[30:31], v[232:233]
	v_pk_add_f32 v[32:33], v[32:33], v[234:235]
	s_waitcnt vmcnt(2)
	v_pk_add_f32 v[26:27], v[26:27], v[236:237]
	v_pk_add_f32 v[28:29], v[28:29], v[238:239]
	s_waitcnt vmcnt(1)
	v_pk_add_f32 v[14:15], v[14:15], v[240:241]
	v_pk_add_f32 v[16:17], v[16:17], v[242:243]
	s_waitcnt vmcnt(0)
	v_pk_add_f32 v[10:11], v[10:11], v[136:137]
	v_pk_add_f32 v[12:13], v[12:13], v[138:139]
	global_load_dwordx4 v[216:219], v250, s[100:101] sc0 sc1
	global_load_dwordx4 v[220:223], v250, s[100:101] offset:1024 sc0 sc1
	global_load_dwordx4 v[224:227], v250, s[100:101] offset:2048 sc0 sc1
	global_load_dwordx4 v[228:231], v250, s[100:101] offset:3072 sc0 sc1
	s_add_u32 s100, s100, 0x1000
	s_addc_u32 s101, s101, 0
	global_load_dwordx4 v[232:235], v250, s[100:101] sc0 sc1
	global_load_dwordx4 v[236:239], v250, s[100:101] offset:1024 sc0 sc1
	global_load_dwordx4 v[240:243], v250, s[100:101] offset:2048 sc0 sc1
	global_load_dwordx4 v[136:139], v250, s[100:101] offset:3072 sc0 sc1
	s_add_u32 s100, s100, 0x1000
	s_addc_u32 s101, s101, 0
	s_waitcnt vmcnt(7)
	v_pk_add_f32 v[54:55], v[54:55], v[216:217]
	v_pk_add_f32 v[56:57], v[56:57], v[218:219]
	s_waitcnt vmcnt(6)
	v_pk_add_f32 v[50:51], v[50:51], v[220:221]
	v_pk_add_f32 v[52:53], v[52:53], v[222:223]
	s_waitcnt vmcnt(5)
	v_pk_add_f32 v[38:39], v[38:39], v[224:225]
	v_pk_add_f32 v[40:41], v[40:41], v[226:227]
	s_waitcnt vmcnt(4)
	v_pk_add_f32 v[34:35], v[34:35], v[228:229]
	v_pk_add_f32 v[36:37], v[36:37], v[230:231]
	s_waitcnt vmcnt(3)
	v_pk_add_f32 v[22:23], v[22:23], v[232:233]
	v_pk_add_f32 v[24:25], v[24:25], v[234:235]
	s_waitcnt vmcnt(2)
	v_pk_add_f32 v[18:19], v[18:19], v[236:237]
	v_pk_add_f32 v[20:21], v[20:21], v[238:239]
	s_waitcnt vmcnt(1)
	v_pk_add_f32 v[6:7], v[6:7], v[240:241]
	v_pk_add_f32 v[8:9], v[8:9], v[242:243]
	s_waitcnt vmcnt(0)
	v_pk_add_f32 v[2:3], v[2:3], v[136:137]
	v_pk_add_f32 v[4:5], v[4:5], v[138:139]
	s_branch .Lmy_ik_norm
